# v105 + bf16 residual stream kept cacheable between row_pass1 (store without nt) and row_pass2 (load without nt)
# baseline (speedup 1.0000x reference)
; __device__ __forceinline__ unsigned cvtpk(float lo, float hi) { f32x2_t v = {lo, hi}; bf16x2_t b = __builtin_convertvector(v, bf16x2_t); return __builtin_bit_cast(unsigned, b); }
; #define NTL(p) __builtin_nontemporal_load(&(p))
; #define NTS(v, p) __builtin_nontemporal_store((v), &(p))
; __device__ __forceinline__ float bf_lo(unsigned u) { return __uint_as_float(u << 16); }
; __device__ __forceinline__ float bf_hi(unsigned u) { return __uint_as_float(u & 0xffff0000u); }
; template <bool HAS_H, bool XIN_BF, bool XOUT_BF>
; __device__ __forceinline__ void row_pass(const bf16_t* y, const void* xin, void* xout, const float* g_post, const float* g_pre, bf16_t* hout, int G, int blk) {
;     ...
;         for (int j = 0; j < 8; ++j) { const u32x2 w = NTL(yr[64 * j]); yv[j] = (f32x4){bf_lo(w.x), bf_hi(w.x), bf_lo(w.y), bf_hi(w.y)};
;             if (XIN_BF) { const u32x2 xw = NTL(xrb[64 * j]); xv[j] = (f32x4){bf_lo(xw.x), bf_hi(xw.x), bf_lo(xw.y), bf_hi(xw.y)}; } else xv[j] = NTL(xr[64 * j]);
;             s += (yv[j].x * yv[j].x + yv[j].y * yv[j].y) + (yv[j].z * yv[j].z + yv[j].w * yv[j].w); }
;         const float r = 1.0f / sqrtf(wave_sum(s) * (1.0f / DM) + EPS);
;         const f32x4* gp = (const f32x4*)g_post + lane;
;         f32x4* xo = (f32x4*)((float*)xout + (size_t)row * DM) + lane;
;         u32x2* xob = (u32x2*)((bf16_t*)xout + (size_t)row * DM) + lane;
;         float s1 = 0.f;
; #pragma unroll
;         for (int j = 0; j < 8; ++j) { const f32x4 gv = gp[64 * j]; xv[j] = xv[j] + yv[j] * r * gv;
;             if (XOUT_BF) { u32x2 w; w.x = cvtpk(xv[j].x, xv[j].y); w.y = cvtpk(xv[j].z, xv[j].w); NTS(w, xob[64 * j]); } else NTS(xv[j], xo[64 * j]);
;             s1 += (xv[j].x * xv[j].x + xv[j].y * xv[j].y) + (xv[j].z * xv[j].z + xv[j].w * xv[j].w); }
.Lrow_rp1_compA:
	v_lshlrev_b32_e32 v184, 16, v10
	v_and_b32_e32 v185, 0xffff0000, v10
	v_lshlrev_b32_e32 v186, 16, v11
	v_and_b32_e32 v187, 0xffff0000, v11
	v_lshlrev_b32_e32 v192, 16, v80
	v_and_b32_e32 v193, 0xffff0000, v80
	v_lshlrev_b32_e32 v194, 16, v81
	v_and_b32_e32 v195, 0xffff0000, v81
	v_lshlrev_b32_e32 v196, 16, v82
	v_and_b32_e32 v197, 0xffff0000, v82
	v_lshlrev_b32_e32 v198, 16, v83
	v_and_b32_e32 v199, 0xffff0000, v83
	v_lshlrev_b32_e32 v200, 16, v84
	v_and_b32_e32 v201, 0xffff0000, v84
	v_lshlrev_b32_e32 v202, 16, v85
	v_and_b32_e32 v203, 0xffff0000, v85
	v_lshlrev_b32_e32 v204, 16, v86
	v_and_b32_e32 v205, 0xffff0000, v86
	v_lshlrev_b32_e32 v206, 16, v87
	v_and_b32_e32 v207, 0xffff0000, v87
	v_lshlrev_b32_e32 v208, 16, v88
	v_and_b32_e32 v209, 0xffff0000, v88
	v_lshlrev_b32_e32 v210, 16, v89
	v_and_b32_e32 v211, 0xffff0000, v89
	v_lshlrev_b32_e32 v212, 16, v90
	v_and_b32_e32 v213, 0xffff0000, v90
	v_lshlrev_b32_e32 v214, 16, v91
	v_and_b32_e32 v215, 0xffff0000, v91
	v_lshlrev_b32_e32 v216, 16, v92
	v_and_b32_e32 v217, 0xffff0000, v92
	v_lshlrev_b32_e32 v218, 16, v93
	v_and_b32_e32 v219, 0xffff0000, v93
	v_pk_mul_f32 v[110:111], v[184:185], v[184:185]
	v_pk_mul_f32 v[130:131], v[186:187], v[186:187]
	v_pk_fma_f32 v[110:111], v[192:193], v[192:193], v[110:111]
	v_pk_fma_f32 v[130:131], v[194:195], v[194:195], v[130:131]
	v_pk_fma_f32 v[110:111], v[196:197], v[196:197], v[110:111]
	v_pk_fma_f32 v[130:131], v[198:199], v[198:199], v[130:131]
	v_pk_fma_f32 v[110:111], v[200:201], v[200:201], v[110:111]
	v_pk_fma_f32 v[130:131], v[202:203], v[202:203], v[130:131]
	v_pk_fma_f32 v[110:111], v[204:205], v[204:205], v[110:111]
	v_pk_fma_f32 v[130:131], v[206:207], v[206:207], v[130:131]
	v_pk_fma_f32 v[110:111], v[208:209], v[208:209], v[110:111]
	v_pk_fma_f32 v[130:131], v[210:211], v[210:211], v[130:131]
	v_pk_fma_f32 v[110:111], v[212:213], v[212:213], v[110:111]
	v_pk_fma_f32 v[130:131], v[214:215], v[214:215], v[130:131]
	v_pk_fma_f32 v[110:111], v[216:217], v[216:217], v[110:111]
	v_pk_fma_f32 v[130:131], v[218:219], v[218:219], v[130:131]
	v_pk_add_f32 v[110:111], v[110:111], v[130:131]
	s_nop 0
	v_add_f32_e32 v161, v110, v111
	ds_bpermute_b32 v188, v4, v161
	s_waitcnt lgkmcnt(0)
	v_add_f32_e32 v161, v161, v188
	ds_bpermute_b32 v188, v5, v161
	s_waitcnt lgkmcnt(0)
	v_add_f32_e32 v161, v161, v188
	ds_bpermute_b32 v188, v6, v161
	s_waitcnt lgkmcnt(0)
	v_add_f32_e32 v161, v161, v188
	ds_bpermute_b32 v188, v7, v161
	s_waitcnt lgkmcnt(0)
	v_add_f32_e32 v161, v161, v188
	ds_bpermute_b32 v188, v8, v161
	s_waitcnt lgkmcnt(0)
	v_add_f32_e32 v161, v161, v188
	ds_bpermute_b32 v188, v9, v161
	s_waitcnt lgkmcnt(0)
	v_add_f32_e32 v161, v161, v188
	v_fmamk_f32 v161, v161, 0x3a000000, v2
	v_mul_f32_e32 v189, 0x4f800000, v161
	v_cmp_gt_f32_e32 vcc, s85, v161
	s_nop 1
	v_cndmask_b32_e32 v161, v161, v189, vcc
	v_sqrt_f32_e32 v189, v161
	s_nop 0
	v_add_u32_e32 v191, -1, v189
	v_add_u32_e32 v234, 1, v189
	v_fma_f32 v235, -v191, v189, v161
	v_fma_f32 v188, -v234, v189, v161
	v_cmp_ge_f32_e64 s[80:81], 0, v235
	s_nop 1
	v_cndmask_b32_e64 v189, v189, v191, s[80:81]
	v_cmp_lt_f32_e64 s[80:81], 0, v188
	s_nop 1
	v_cndmask_b32_e64 v189, v189, v234, s[80:81]
	v_mul_f32_e32 v191, 0x37800000, v189
	v_cndmask_b32_e32 v189, v189, v191, vcc
	v_cmp_class_f32_e32 vcc, v161, v3
	s_nop 1
	v_cndmask_b32_e32 v161, v189, v161, vcc
	v_div_scale_f32 v189, s[80:81], v161, v161, 1.0
	v_rcp_f32_e32 v234, v189
	v_div_scale_f32 v191, vcc, 1.0, v161, 1.0
	v_fma_f32 v235, -v189, v234, 1.0
	v_fmac_f32_e32 v234, v235, v234
	v_mul_f32_e32 v235, v191, v234
	v_fma_f32 v188, -v189, v235, v191
	v_fmac_f32_e32 v235, v188, v234
	v_fma_f32 v189, -v189, v235, v191
	v_div_fmas_f32 v189, v189, v234, v235
	v_div_fixup_f32 v220, v189, v161, 1.0
	v_pk_mul_f32 v[222:223], v[184:185], v[220:221] op_sel_hi:[1,0]
	v_pk_mul_f32 v[224:225], v[186:187], v[220:221] op_sel_hi:[1,0]
	v_pk_fma_f32 v[112:113], v[12:13], v[222:223], v[112:113]
	v_pk_fma_f32 v[114:115], v[14:15], v[224:225], v[114:115]
	v_cvt_pk_bf16_f32 v226, v112, v113
	v_cvt_pk_bf16_f32 v227, v114, v115
	global_store_dwordx2 v0, v[226:227], s[70:71] offset:0
	v_pk_mul_f32 v[222:223], v[192:193], v[220:221] op_sel_hi:[1,0]
	v_pk_mul_f32 v[224:225], v[194:195], v[220:221] op_sel_hi:[1,0]
	v_pk_fma_f32 v[116:117], v[16:17], v[222:223], v[116:117]
	v_pk_fma_f32 v[118:119], v[18:19], v[224:225], v[118:119]
	v_cvt_pk_bf16_f32 v228, v116, v117
	v_cvt_pk_bf16_f32 v229, v118, v119
	global_store_dwordx2 v0, v[228:229], s[70:71] offset:512
	v_pk_mul_f32 v[222:223], v[196:197], v[220:221] op_sel_hi:[1,0]
	v_pk_mul_f32 v[224:225], v[198:199], v[220:221] op_sel_hi:[1,0]
	v_pk_fma_f32 v[120:121], v[20:21], v[222:223], v[120:121]
	v_pk_fma_f32 v[122:123], v[22:23], v[224:225], v[122:123]
	v_cvt_pk_bf16_f32 v230, v120, v121
	v_cvt_pk_bf16_f32 v231, v122, v123
	global_store_dwordx2 v0, v[230:231], s[70:71] offset:1024
	v_pk_mul_f32 v[222:223], v[200:201], v[220:221] op_sel_hi:[1,0]
	v_pk_mul_f32 v[224:225], v[202:203], v[220:221] op_sel_hi:[1,0]
	v_pk_fma_f32 v[124:125], v[24:25], v[222:223], v[124:125]
	v_pk_fma_f32 v[126:127], v[26:27], v[224:225], v[126:127]
	v_cvt_pk_bf16_f32 v232, v124, v125
	v_cvt_pk_bf16_f32 v233, v126, v127
	global_store_dwordx2 v0, v[232:233], s[70:71] offset:1536
	v_pk_mul_f32 v[222:223], v[204:205], v[220:221] op_sel_hi:[1,0]
	v_pk_mul_f32 v[224:225], v[206:207], v[220:221] op_sel_hi:[1,0]
	v_pk_fma_f32 v[132:133], v[28:29], v[222:223], v[132:133]
	v_pk_fma_f32 v[134:135], v[30:31], v[224:225], v[134:135]
	v_cvt_pk_bf16_f32 v226, v132, v133
	v_cvt_pk_bf16_f32 v227, v134, v135
	global_store_dwordx2 v0, v[226:227], s[70:71] offset:2048
; __device__ __forceinline__ unsigned cvtpk(float lo, float hi) { f32x2_t v = {lo, hi}; bf16x2_t b = __builtin_convertvector(v, bf16x2_t); return __builtin_bit_cast(unsigned, b); }
; #define NTS(v, p) __builtin_nontemporal_store((v), &(p))
; template <bool HAS_H, bool XIN_BF, bool XOUT_BF>
; __device__ __forceinline__ void row_pass(const bf16_t* y, const void* xin, void* xout, const float* g_post, const float* g_pre, bf16_t* hout, int G, int blk) {
;     ...
;         for (int j = 0; j < 8; ++j) { const f32x4 gv = gp[64 * j]; xv[j] = xv[j] + yv[j] * r * gv;
;             if (XOUT_BF) { u32x2 w; w.x = cvtpk(xv[j].x, xv[j].y); w.y = cvtpk(xv[j].z, xv[j].w); NTS(w, xob[64 * j]); } else NTS(xv[j], xo[64 * j]);
;             s1 += (xv[j].x * xv[j].x + xv[j].y * xv[j].y) + (xv[j].z * xv[j].z + xv[j].w * xv[j].w); }
;         if (HAS_H) {
;             const float r1 = 1.0f / sqrtf(wave_sum(s1) * (1.0f / DM) + EPS);
;             const f32x4* gq = (const f32x4*)g_pre + lane;
;             u32x2* ho = (u32x2*)(hout + (size_t)row * DM) + lane;
; #pragma unroll
;             for (int j = 0; j < 8; ++j) { const f32x4 gv = gq[64 * j]; u32x2 w; w.x = cvtpk(xv[j].x * r1 * gv.x, xv[j].y * r1 * gv.y); w.y = cvtpk(xv[j].z * r1 * gv.z, xv[j].w * r1 * gv.w); ho[64 * j] = w; }
;         }
	v_pk_mul_f32 v[222:223], v[208:209], v[220:221] op_sel_hi:[1,0]
	v_pk_mul_f32 v[224:225], v[210:211], v[220:221] op_sel_hi:[1,0]
	v_pk_fma_f32 v[136:137], v[36:37], v[222:223], v[136:137]
	v_pk_fma_f32 v[138:139], v[38:39], v[224:225], v[138:139]
	v_cvt_pk_bf16_f32 v228, v136, v137
	v_cvt_pk_bf16_f32 v229, v138, v139
	global_store_dwordx2 v0, v[228:229], s[70:71] offset:2560
	v_pk_mul_f32 v[222:223], v[212:213], v[220:221] op_sel_hi:[1,0]
	v_pk_mul_f32 v[224:225], v[214:215], v[220:221] op_sel_hi:[1,0]
	v_pk_fma_f32 v[140:141], v[40:41], v[222:223], v[140:141]
	v_pk_fma_f32 v[142:143], v[42:43], v[224:225], v[142:143]
	v_cvt_pk_bf16_f32 v230, v140, v141
	v_cvt_pk_bf16_f32 v231, v142, v143
	global_store_dwordx2 v0, v[230:231], s[70:71] offset:3072
	v_pk_mul_f32 v[222:223], v[216:217], v[220:221] op_sel_hi:[1,0]
	v_pk_mul_f32 v[224:225], v[218:219], v[220:221] op_sel_hi:[1,0]
	v_pk_fma_f32 v[144:145], v[44:45], v[222:223], v[144:145]
	v_pk_fma_f32 v[146:147], v[46:47], v[224:225], v[146:147]
	v_cvt_pk_bf16_f32 v232, v144, v145
	v_cvt_pk_bf16_f32 v233, v146, v147
	global_store_dwordx2 v0, v[232:233], s[70:71] offset:3584
	s_add_u32 s70, s70, s62
	s_addc_u32 s71, s71, 0
	v_pk_mul_f32 v[110:111], v[112:113], v[112:113]
	v_pk_mul_f32 v[130:131], v[114:115], v[114:115]
	v_pk_fma_f32 v[110:111], v[116:117], v[116:117], v[110:111]
	v_pk_fma_f32 v[130:131], v[118:119], v[118:119], v[130:131]
	v_pk_fma_f32 v[110:111], v[120:121], v[120:121], v[110:111]
	v_pk_fma_f32 v[130:131], v[122:123], v[122:123], v[130:131]
	v_pk_fma_f32 v[110:111], v[124:125], v[124:125], v[110:111]
	v_pk_fma_f32 v[130:131], v[126:127], v[126:127], v[130:131]
	v_pk_fma_f32 v[110:111], v[132:133], v[132:133], v[110:111]
	v_pk_fma_f32 v[130:131], v[134:135], v[134:135], v[130:131]
	v_pk_fma_f32 v[110:111], v[136:137], v[136:137], v[110:111]
	v_pk_fma_f32 v[130:131], v[138:139], v[138:139], v[130:131]
	v_pk_fma_f32 v[110:111], v[140:141], v[140:141], v[110:111]
	v_pk_fma_f32 v[130:131], v[142:143], v[142:143], v[130:131]
	v_pk_fma_f32 v[110:111], v[144:145], v[144:145], v[110:111]
	v_pk_fma_f32 v[130:131], v[146:147], v[146:147], v[130:131]
	v_pk_add_f32 v[110:111], v[110:111], v[130:131]
	s_nop 0
	v_add_f32_e32 v161, v110, v111
	ds_bpermute_b32 v188, v4, v161
	s_waitcnt lgkmcnt(0)
	v_add_f32_e32 v161, v161, v188
	ds_bpermute_b32 v188, v5, v161
	s_waitcnt lgkmcnt(0)
	v_add_f32_e32 v161, v161, v188
	ds_bpermute_b32 v188, v6, v161
	s_waitcnt lgkmcnt(0)
	v_add_f32_e32 v161, v161, v188
	ds_bpermute_b32 v188, v7, v161
	s_waitcnt lgkmcnt(0)
	v_add_f32_e32 v161, v161, v188
	ds_bpermute_b32 v188, v8, v161
	s_waitcnt lgkmcnt(0)
	v_add_f32_e32 v161, v161, v188
	ds_bpermute_b32 v188, v9, v161
	s_waitcnt lgkmcnt(0)
	v_add_f32_e32 v161, v161, v188
	v_fmamk_f32 v161, v161, 0x3a000000, v2
	v_mul_f32_e32 v189, 0x4f800000, v161
	v_cmp_gt_f32_e32 vcc, s85, v161
	s_nop 1
	v_cndmask_b32_e32 v161, v161, v189, vcc
	v_sqrt_f32_e32 v189, v161
	s_nop 0
	v_add_u32_e32 v191, -1, v189
	v_add_u32_e32 v234, 1, v189
	v_fma_f32 v235, -v191, v189, v161
	v_fma_f32 v188, -v234, v189, v161
	v_cmp_ge_f32_e64 s[80:81], 0, v235
	s_nop 1
	v_cndmask_b32_e64 v189, v189, v191, s[80:81]
	v_cmp_lt_f32_e64 s[80:81], 0, v188
	s_nop 1
	v_cndmask_b32_e64 v189, v189, v234, s[80:81]
	v_mul_f32_e32 v191, 0x37800000, v189
	v_cndmask_b32_e32 v189, v189, v191, vcc
	v_cmp_class_f32_e32 vcc, v161, v3
	s_nop 1
	v_cndmask_b32_e32 v161, v189, v161, vcc
	v_div_scale_f32 v189, s[80:81], v161, v161, 1.0
	v_rcp_f32_e32 v234, v189
	v_div_scale_f32 v191, vcc, 1.0, v161, 1.0
	v_fma_f32 v235, -v189, v234, 1.0
	v_fmac_f32_e32 v234, v235, v234
	v_mul_f32_e32 v235, v191, v234
	v_fma_f32 v188, -v189, v235, v191
	v_fmac_f32_e32 v235, v188, v234
	v_fma_f32 v189, -v189, v235, v191
	v_div_fmas_f32 v189, v189, v234, v235
	v_div_fixup_f32 v220, v189, v161, 1.0
	v_pk_mul_f32 v[222:223], v[112:113], v[220:221] op_sel_hi:[1,0]
	v_pk_mul_f32 v[224:225], v[114:115], v[220:221] op_sel_hi:[1,0]
	v_pk_mul_f32 v[222:223], v[48:49], v[222:223]
	v_pk_mul_f32 v[224:225], v[50:51], v[224:225]
	v_cvt_pk_bf16_f32 v226, v222, v223
	v_cvt_pk_bf16_f32 v227, v224, v225
	global_store_dwordx2 v0, v[226:227], s[78:79] offset:0
	v_pk_mul_f32 v[222:223], v[116:117], v[220:221] op_sel_hi:[1,0]
	v_pk_mul_f32 v[224:225], v[118:119], v[220:221] op_sel_hi:[1,0]
	v_pk_mul_f32 v[222:223], v[52:53], v[222:223]
	v_pk_mul_f32 v[224:225], v[54:55], v[224:225]
	v_cvt_pk_bf16_f32 v228, v222, v223
	v_cvt_pk_bf16_f32 v229, v224, v225
	global_store_dwordx2 v0, v[228:229], s[78:79] offset:512
	v_pk_mul_f32 v[222:223], v[120:121], v[220:221] op_sel_hi:[1,0]
	v_pk_mul_f32 v[224:225], v[122:123], v[220:221] op_sel_hi:[1,0]
	v_pk_mul_f32 v[222:223], v[56:57], v[222:223]
	v_pk_mul_f32 v[224:225], v[58:59], v[224:225]
	v_cvt_pk_bf16_f32 v230, v222, v223
	v_cvt_pk_bf16_f32 v231, v224, v225
	global_store_dwordx2 v0, v[230:231], s[78:79] offset:1024
	v_pk_mul_f32 v[222:223], v[124:125], v[220:221] op_sel_hi:[1,0]
	v_pk_mul_f32 v[224:225], v[126:127], v[220:221] op_sel_hi:[1,0]
	v_pk_mul_f32 v[222:223], v[60:61], v[222:223]
	v_pk_mul_f32 v[224:225], v[62:63], v[224:225]
	v_cvt_pk_bf16_f32 v232, v222, v223
	v_cvt_pk_bf16_f32 v233, v224, v225
	global_store_dwordx2 v0, v[232:233], s[78:79] offset:1536
	v_pk_mul_f32 v[222:223], v[132:133], v[220:221] op_sel_hi:[1,0]
	v_pk_mul_f32 v[224:225], v[134:135], v[220:221] op_sel_hi:[1,0]
	v_pk_mul_f32 v[222:223], v[64:65], v[222:223]
	v_pk_mul_f32 v[224:225], v[66:67], v[224:225]
	v_cvt_pk_bf16_f32 v226, v222, v223
	v_cvt_pk_bf16_f32 v227, v224, v225
	global_store_dwordx2 v0, v[226:227], s[78:79] offset:2048
	v_pk_mul_f32 v[222:223], v[136:137], v[220:221] op_sel_hi:[1,0]
	v_pk_mul_f32 v[224:225], v[138:139], v[220:221] op_sel_hi:[1,0]
	v_pk_mul_f32 v[222:223], v[68:69], v[222:223]
	v_pk_mul_f32 v[224:225], v[70:71], v[224:225]
	v_cvt_pk_bf16_f32 v228, v222, v223
	v_cvt_pk_bf16_f32 v229, v224, v225
	global_store_dwordx2 v0, v[228:229], s[78:79] offset:2560
	v_pk_mul_f32 v[222:223], v[140:141], v[220:221] op_sel_hi:[1,0]
	v_pk_mul_f32 v[224:225], v[142:143], v[220:221] op_sel_hi:[1,0]
	v_pk_mul_f32 v[222:223], v[72:73], v[222:223]
	v_pk_mul_f32 v[224:225], v[74:75], v[224:225]
	v_cvt_pk_bf16_f32 v230, v222, v223
	v_cvt_pk_bf16_f32 v231, v224, v225
	global_store_dwordx2 v0, v[230:231], s[78:79] offset:3072
	v_pk_mul_f32 v[222:223], v[144:145], v[220:221] op_sel_hi:[1,0]
	v_pk_mul_f32 v[224:225], v[146:147], v[220:221] op_sel_hi:[1,0]
	v_pk_mul_f32 v[222:223], v[76:77], v[222:223]
	v_pk_mul_f32 v[224:225], v[78:79], v[224:225]
	v_cvt_pk_bf16_f32 v232, v222, v223
	v_cvt_pk_bf16_f32 v233, v224, v225
	global_store_dwordx2 v0, v[232:233], s[78:79] offset:3584
	s_add_u32 s78, s78, s62
	s_addc_u32 s79, s79, 0
	s_mov_b32 s32, s84
	s_cmp_lt_u32 s32, 0x8000
	s_cbranch_scc0 .Lrow_rp1_done
; #define NTL(p) __builtin_nontemporal_load(&(p))
; __device__ __forceinline__ float bf_lo(unsigned u) { return __uint_as_float(u << 16); }
; __device__ __forceinline__ float bf_hi(unsigned u) { return __uint_as_float(u & 0xffff0000u); }
; template <bool HAS_H, bool XIN_BF, bool XOUT_BF>
; __device__ __forceinline__ void row_pass(const bf16_t* y, const void* xin, void* xout, const float* g_post, const float* g_pre, bf16_t* hout, int G, int blk) {
;     ...
;     for (int row = gw; row < MT; row += NGW) {
;         const u32x2* yr = (const u32x2*)(y + (size_t)row * DM) + lane;
;         const f32x4* xr = (const f32x4*)((const float*)xin + (size_t)row * DM) + lane;
;         const u32x2* xrb = (const u32x2*)((const bf16_t*)xin + (size_t)row * DM) + lane;
;         f32x4 yv[8], xv[8]; float s = 0.f;
; #pragma unroll
;         for (int j = 0; j < 8; ++j) { const u32x2 w = NTL(yr[64 * j]); yv[j] = (f32x4){bf_lo(w.x), bf_hi(w.x), bf_lo(w.y), bf_hi(w.y)};
;             if (XIN_BF) { const u32x2 xw = NTL(xrb[64 * j]); xv[j] = (f32x4){bf_lo(xw.x), bf_hi(xw.x), bf_lo(xw.y), bf_hi(xw.y)}; } else xv[j] = NTL(xr[64 * j]);
;             s += (yv[j].x * yv[j].x + yv[j].y * yv[j].y) + (yv[j].z * yv[j].z + yv[j].w * yv[j].w); }
	s_add_u32 s84, s32, s94
	s_cmp_lt_u32 s84, 0x8000
	s_cbranch_scc0 .Lrow_rp1_lastB
	global_load_dwordx2 v[10:11], v0, s[24:25] offset:0 nt
	global_load_dwordx2 v[80:81], v0, s[24:25] offset:512 nt
	global_load_dwordx2 v[82:83], v0, s[24:25] offset:1024 nt
	global_load_dwordx2 v[84:85], v0, s[24:25] offset:1536 nt
	global_load_dwordx2 v[86:87], v0, s[24:25] offset:2048 nt
	global_load_dwordx2 v[88:89], v0, s[24:25] offset:2560 nt
	global_load_dwordx2 v[90:91], v0, s[24:25] offset:3072 nt
	global_load_dwordx2 v[92:93], v0, s[24:25] offset:3584 nt
	global_load_dwordx4 v[112:115], v1, s[26:27] offset:-4096 nt
	global_load_dwordx4 v[116:119], v1, s[26:27] offset:-3072 nt
	global_load_dwordx4 v[120:123], v1, s[26:27] offset:-2048 nt
	global_load_dwordx4 v[124:127], v1, s[26:27] offset:-1024 nt
	global_load_dwordx4 v[132:135], v1, s[26:27] offset:0 nt
	global_load_dwordx4 v[136:139], v1, s[26:27] offset:1024 nt
	global_load_dwordx4 v[140:143], v1, s[26:27] offset:2048 nt
	global_load_dwordx4 v[144:147], v1, s[26:27] offset:3072 nt
	s_add_u32 s24, s24, s62
	s_addc_u32 s25, s25, 0
	s_add_u32 s26, s26, s63
	s_addc_u32 s27, s27, 0
	s_waitcnt vmcnt(32)
	s_branch .Lrow_rp1_compB

; __device__ __forceinline__ unsigned cvtpk(float lo, float hi) { f32x2_t v = {lo, hi}; bf16x2_t b = __builtin_convertvector(v, bf16x2_t); return __builtin_bit_cast(unsigned, b); }
; #define NTL(p) __builtin_nontemporal_load(&(p))
; #define NTS(v, p) __builtin_nontemporal_store((v), &(p))
; __device__ __forceinline__ float bf_lo(unsigned u) { return __uint_as_float(u << 16); }
; __device__ __forceinline__ float bf_hi(unsigned u) { return __uint_as_float(u & 0xffff0000u); }
; template <bool HAS_H, bool XIN_BF, bool XOUT_BF>
; __device__ __forceinline__ void row_pass(const bf16_t* y, const void* xin, void* xout, const float* g_post, const float* g_pre, bf16_t* hout, int G, int blk) {
;     ...
;         for (int j = 0; j < 8; ++j) { const u32x2 w = NTL(yr[64 * j]); yv[j] = (f32x4){bf_lo(w.x), bf_hi(w.x), bf_lo(w.y), bf_hi(w.y)};
;             if (XIN_BF) { const u32x2 xw = NTL(xrb[64 * j]); xv[j] = (f32x4){bf_lo(xw.x), bf_hi(xw.x), bf_lo(xw.y), bf_hi(xw.y)}; } else xv[j] = NTL(xr[64 * j]);
;             s += (yv[j].x * yv[j].x + yv[j].y * yv[j].y) + (yv[j].z * yv[j].z + yv[j].w * yv[j].w); }
;         const float r = 1.0f / sqrtf(wave_sum(s) * (1.0f / DM) + EPS);
;         const f32x4* gp = (const f32x4*)g_post + lane;
;         f32x4* xo = (f32x4*)((float*)xout + (size_t)row * DM) + lane;
;         u32x2* xob = (u32x2*)((bf16_t*)xout + (size_t)row * DM) + lane;
;         float s1 = 0.f;
; #pragma unroll
;         for (int j = 0; j < 8; ++j) { const f32x4 gv = gp[64 * j]; xv[j] = xv[j] + yv[j] * r * gv;
;             if (XOUT_BF) { u32x2 w; w.x = cvtpk(xv[j].x, xv[j].y); w.y = cvtpk(xv[j].z, xv[j].w); NTS(w, xob[64 * j]); } else NTS(xv[j], xo[64 * j]);
;             s1 += (xv[j].x * xv[j].x + xv[j].y * xv[j].y) + (xv[j].z * xv[j].z + xv[j].w * xv[j].w); }
.Lrow_rp1_compB:
	v_lshlrev_b32_e32 v184, 16, v94
	v_and_b32_e32 v185, 0xffff0000, v94
	v_lshlrev_b32_e32 v186, 16, v95
	v_and_b32_e32 v187, 0xffff0000, v95
	v_lshlrev_b32_e32 v192, 16, v96
	v_and_b32_e32 v193, 0xffff0000, v96
	v_lshlrev_b32_e32 v194, 16, v97
	v_and_b32_e32 v195, 0xffff0000, v97
	v_lshlrev_b32_e32 v196, 16, v98
	v_and_b32_e32 v197, 0xffff0000, v98
	v_lshlrev_b32_e32 v198, 16, v99
	v_and_b32_e32 v199, 0xffff0000, v99
	v_lshlrev_b32_e32 v200, 16, v100
	v_and_b32_e32 v201, 0xffff0000, v100
	v_lshlrev_b32_e32 v202, 16, v101
	v_and_b32_e32 v203, 0xffff0000, v101
	v_lshlrev_b32_e32 v204, 16, v102
	v_and_b32_e32 v205, 0xffff0000, v102
	v_lshlrev_b32_e32 v206, 16, v103
	v_and_b32_e32 v207, 0xffff0000, v103
	v_lshlrev_b32_e32 v208, 16, v104
	v_and_b32_e32 v209, 0xffff0000, v104
	v_lshlrev_b32_e32 v210, 16, v105
	v_and_b32_e32 v211, 0xffff0000, v105
	v_lshlrev_b32_e32 v212, 16, v106
	v_and_b32_e32 v213, 0xffff0000, v106
	v_lshlrev_b32_e32 v214, 16, v107
	v_and_b32_e32 v215, 0xffff0000, v107
	v_lshlrev_b32_e32 v216, 16, v108
	v_and_b32_e32 v217, 0xffff0000, v108
	v_lshlrev_b32_e32 v218, 16, v109
	v_and_b32_e32 v219, 0xffff0000, v109
	v_pk_mul_f32 v[110:111], v[184:185], v[184:185]
	v_pk_mul_f32 v[130:131], v[186:187], v[186:187]
	v_pk_fma_f32 v[110:111], v[192:193], v[192:193], v[110:111]
	v_pk_fma_f32 v[130:131], v[194:195], v[194:195], v[130:131]
	v_pk_fma_f32 v[110:111], v[196:197], v[196:197], v[110:111]
	v_pk_fma_f32 v[130:131], v[198:199], v[198:199], v[130:131]
	v_pk_fma_f32 v[110:111], v[200:201], v[200:201], v[110:111]
	v_pk_fma_f32 v[130:131], v[202:203], v[202:203], v[130:131]
	v_pk_fma_f32 v[110:111], v[204:205], v[204:205], v[110:111]
	v_pk_fma_f32 v[130:131], v[206:207], v[206:207], v[130:131]
	v_pk_fma_f32 v[110:111], v[208:209], v[208:209], v[110:111]
	v_pk_fma_f32 v[130:131], v[210:211], v[210:211], v[130:131]
	v_pk_fma_f32 v[110:111], v[212:213], v[212:213], v[110:111]
	v_pk_fma_f32 v[130:131], v[214:215], v[214:215], v[130:131]
	v_pk_fma_f32 v[110:111], v[216:217], v[216:217], v[110:111]
	v_pk_fma_f32 v[130:131], v[218:219], v[218:219], v[130:131]
	v_pk_add_f32 v[110:111], v[110:111], v[130:131]
	s_nop 0
	v_add_f32_e32 v161, v110, v111
	ds_bpermute_b32 v188, v4, v161
	s_waitcnt lgkmcnt(0)
	v_add_f32_e32 v161, v161, v188
	ds_bpermute_b32 v188, v5, v161
	s_waitcnt lgkmcnt(0)
	v_add_f32_e32 v161, v161, v188
	ds_bpermute_b32 v188, v6, v161
	s_waitcnt lgkmcnt(0)
	v_add_f32_e32 v161, v161, v188
	ds_bpermute_b32 v188, v7, v161
	s_waitcnt lgkmcnt(0)
	v_add_f32_e32 v161, v161, v188
	ds_bpermute_b32 v188, v8, v161
	s_waitcnt lgkmcnt(0)
	v_add_f32_e32 v161, v161, v188
	ds_bpermute_b32 v188, v9, v161
	s_waitcnt lgkmcnt(0)
	v_add_f32_e32 v161, v161, v188
	v_fmamk_f32 v161, v161, 0x3a000000, v2
	v_mul_f32_e32 v189, 0x4f800000, v161
	v_cmp_gt_f32_e32 vcc, s85, v161
	s_nop 1
	v_cndmask_b32_e32 v161, v161, v189, vcc
	v_sqrt_f32_e32 v189, v161
	s_nop 0
	v_add_u32_e32 v191, -1, v189
	v_add_u32_e32 v234, 1, v189
	v_fma_f32 v235, -v191, v189, v161
	v_fma_f32 v188, -v234, v189, v161
	v_cmp_ge_f32_e64 s[80:81], 0, v235
	s_nop 1
	v_cndmask_b32_e64 v189, v189, v191, s[80:81]
	v_cmp_lt_f32_e64 s[80:81], 0, v188
	s_nop 1
	v_cndmask_b32_e64 v189, v189, v234, s[80:81]
	v_mul_f32_e32 v191, 0x37800000, v189
	v_cndmask_b32_e32 v189, v189, v191, vcc
	v_cmp_class_f32_e32 vcc, v161, v3
	s_nop 1
	v_cndmask_b32_e32 v161, v189, v161, vcc
	v_div_scale_f32 v189, s[80:81], v161, v161, 1.0
	v_rcp_f32_e32 v234, v189
	v_div_scale_f32 v191, vcc, 1.0, v161, 1.0
	v_fma_f32 v235, -v189, v234, 1.0
	v_fmac_f32_e32 v234, v235, v234
	v_mul_f32_e32 v235, v191, v234
	v_fma_f32 v188, -v189, v235, v191
	v_fmac_f32_e32 v235, v188, v234
	v_fma_f32 v189, -v189, v235, v191
	v_div_fmas_f32 v189, v189, v234, v235
	v_div_fixup_f32 v220, v189, v161, 1.0
	v_pk_mul_f32 v[222:223], v[184:185], v[220:221] op_sel_hi:[1,0]
	v_pk_mul_f32 v[224:225], v[186:187], v[220:221] op_sel_hi:[1,0]
	v_pk_fma_f32 v[148:149], v[12:13], v[222:223], v[148:149]
	v_pk_fma_f32 v[150:151], v[14:15], v[224:225], v[150:151]
	v_cvt_pk_bf16_f32 v226, v148, v149
	v_cvt_pk_bf16_f32 v227, v150, v151
	global_store_dwordx2 v0, v[226:227], s[70:71] offset:0
	v_pk_mul_f32 v[222:223], v[192:193], v[220:221] op_sel_hi:[1,0]
	v_pk_mul_f32 v[224:225], v[194:195], v[220:221] op_sel_hi:[1,0]
	v_pk_fma_f32 v[152:153], v[16:17], v[222:223], v[152:153]
	v_pk_fma_f32 v[154:155], v[18:19], v[224:225], v[154:155]
	v_cvt_pk_bf16_f32 v228, v152, v153
	v_cvt_pk_bf16_f32 v229, v154, v155
	global_store_dwordx2 v0, v[228:229], s[70:71] offset:512
	v_pk_mul_f32 v[222:223], v[196:197], v[220:221] op_sel_hi:[1,0]
	v_pk_mul_f32 v[224:225], v[198:199], v[220:221] op_sel_hi:[1,0]
	v_pk_fma_f32 v[156:157], v[20:21], v[222:223], v[156:157]
	v_pk_fma_f32 v[158:159], v[22:23], v[224:225], v[158:159]
	v_cvt_pk_bf16_f32 v230, v156, v157
	v_cvt_pk_bf16_f32 v231, v158, v159
	global_store_dwordx2 v0, v[230:231], s[70:71] offset:1024
	v_pk_mul_f32 v[222:223], v[200:201], v[220:221] op_sel_hi:[1,0]
	v_pk_mul_f32 v[224:225], v[202:203], v[220:221] op_sel_hi:[1,0]
	v_pk_fma_f32 v[164:165], v[24:25], v[222:223], v[164:165]
	v_pk_fma_f32 v[166:167], v[26:27], v[224:225], v[166:167]
	v_cvt_pk_bf16_f32 v232, v164, v165
	v_cvt_pk_bf16_f32 v233, v166, v167
	global_store_dwordx2 v0, v[232:233], s[70:71] offset:1536
	v_pk_mul_f32 v[222:223], v[204:205], v[220:221] op_sel_hi:[1,0]
	v_pk_mul_f32 v[224:225], v[206:207], v[220:221] op_sel_hi:[1,0]
	v_pk_fma_f32 v[168:169], v[28:29], v[222:223], v[168:169]
	v_pk_fma_f32 v[170:171], v[30:31], v[224:225], v[170:171]
	v_cvt_pk_bf16_f32 v226, v168, v169
	v_cvt_pk_bf16_f32 v227, v170, v171
; __device__ __forceinline__ unsigned cvtpk(float lo, float hi) { f32x2_t v = {lo, hi}; bf16x2_t b = __builtin_convertvector(v, bf16x2_t); return __builtin_bit_cast(unsigned, b); }
; #define NTS(v, p) __builtin_nontemporal_store((v), &(p))
; template <bool HAS_H, bool XIN_BF, bool XOUT_BF>
; __device__ __forceinline__ void row_pass(const bf16_t* y, const void* xin, void* xout, const float* g_post, const float* g_pre, bf16_t* hout, int G, int blk) {
;     ...
;         for (int j = 0; j < 8; ++j) { const f32x4 gv = gp[64 * j]; xv[j] = xv[j] + yv[j] * r * gv;
;             if (XOUT_BF) { u32x2 w; w.x = cvtpk(xv[j].x, xv[j].y); w.y = cvtpk(xv[j].z, xv[j].w); NTS(w, xob[64 * j]); } else NTS(xv[j], xo[64 * j]);
;             s1 += (xv[j].x * xv[j].x + xv[j].y * xv[j].y) + (xv[j].z * xv[j].z + xv[j].w * xv[j].w); }
;         if (HAS_H) {
;             const float r1 = 1.0f / sqrtf(wave_sum(s1) * (1.0f / DM) + EPS);
;             const f32x4* gq = (const f32x4*)g_pre + lane;
;             u32x2* ho = (u32x2*)(hout + (size_t)row * DM) + lane;
; #pragma unroll
;             for (int j = 0; j < 8; ++j) { const f32x4 gv = gq[64 * j]; u32x2 w; w.x = cvtpk(xv[j].x * r1 * gv.x, xv[j].y * r1 * gv.y); w.y = cvtpk(xv[j].z * r1 * gv.z, xv[j].w * r1 * gv.w); ho[64 * j] = w; }
;         }
	global_store_dwordx2 v0, v[226:227], s[70:71] offset:2048
	v_pk_mul_f32 v[222:223], v[208:209], v[220:221] op_sel_hi:[1,0]
	v_pk_mul_f32 v[224:225], v[210:211], v[220:221] op_sel_hi:[1,0]
	v_pk_fma_f32 v[172:173], v[36:37], v[222:223], v[172:173]
	v_pk_fma_f32 v[174:175], v[38:39], v[224:225], v[174:175]
	v_cvt_pk_bf16_f32 v228, v172, v173
	v_cvt_pk_bf16_f32 v229, v174, v175
	global_store_dwordx2 v0, v[228:229], s[70:71] offset:2560
	v_pk_mul_f32 v[222:223], v[212:213], v[220:221] op_sel_hi:[1,0]
	v_pk_mul_f32 v[224:225], v[214:215], v[220:221] op_sel_hi:[1,0]
	v_pk_fma_f32 v[176:177], v[40:41], v[222:223], v[176:177]
	v_pk_fma_f32 v[178:179], v[42:43], v[224:225], v[178:179]
	v_cvt_pk_bf16_f32 v230, v176, v177
	v_cvt_pk_bf16_f32 v231, v178, v179
	global_store_dwordx2 v0, v[230:231], s[70:71] offset:3072
	v_pk_mul_f32 v[222:223], v[216:217], v[220:221] op_sel_hi:[1,0]
	v_pk_mul_f32 v[224:225], v[218:219], v[220:221] op_sel_hi:[1,0]
	v_pk_fma_f32 v[180:181], v[44:45], v[222:223], v[180:181]
	v_pk_fma_f32 v[182:183], v[46:47], v[224:225], v[182:183]
	v_cvt_pk_bf16_f32 v232, v180, v181
	v_cvt_pk_bf16_f32 v233, v182, v183
	global_store_dwordx2 v0, v[232:233], s[70:71] offset:3584
	s_add_u32 s70, s70, s62
	s_addc_u32 s71, s71, 0
	v_pk_mul_f32 v[110:111], v[148:149], v[148:149]
	v_pk_mul_f32 v[130:131], v[150:151], v[150:151]
	v_pk_fma_f32 v[110:111], v[152:153], v[152:153], v[110:111]
	v_pk_fma_f32 v[130:131], v[154:155], v[154:155], v[130:131]
	v_pk_fma_f32 v[110:111], v[156:157], v[156:157], v[110:111]
	v_pk_fma_f32 v[130:131], v[158:159], v[158:159], v[130:131]
	v_pk_fma_f32 v[110:111], v[164:165], v[164:165], v[110:111]
	v_pk_fma_f32 v[130:131], v[166:167], v[166:167], v[130:131]
	v_pk_fma_f32 v[110:111], v[168:169], v[168:169], v[110:111]
	v_pk_fma_f32 v[130:131], v[170:171], v[170:171], v[130:131]
	v_pk_fma_f32 v[110:111], v[172:173], v[172:173], v[110:111]
	v_pk_fma_f32 v[130:131], v[174:175], v[174:175], v[130:131]
	v_pk_fma_f32 v[110:111], v[176:177], v[176:177], v[110:111]
	v_pk_fma_f32 v[130:131], v[178:179], v[178:179], v[130:131]
	v_pk_fma_f32 v[110:111], v[180:181], v[180:181], v[110:111]
	v_pk_fma_f32 v[130:131], v[182:183], v[182:183], v[130:131]
	v_pk_add_f32 v[110:111], v[110:111], v[130:131]
	s_nop 0
	v_add_f32_e32 v161, v110, v111
	ds_bpermute_b32 v188, v4, v161
	s_waitcnt lgkmcnt(0)
	v_add_f32_e32 v161, v161, v188
	ds_bpermute_b32 v188, v5, v161
	s_waitcnt lgkmcnt(0)
	v_add_f32_e32 v161, v161, v188
	ds_bpermute_b32 v188, v6, v161
	s_waitcnt lgkmcnt(0)
	v_add_f32_e32 v161, v161, v188
	ds_bpermute_b32 v188, v7, v161
	s_waitcnt lgkmcnt(0)
	v_add_f32_e32 v161, v161, v188
	ds_bpermute_b32 v188, v8, v161
	s_waitcnt lgkmcnt(0)
	v_add_f32_e32 v161, v161, v188
	ds_bpermute_b32 v188, v9, v161
	s_waitcnt lgkmcnt(0)
	v_add_f32_e32 v161, v161, v188
	v_fmamk_f32 v161, v161, 0x3a000000, v2
	v_mul_f32_e32 v189, 0x4f800000, v161
	v_cmp_gt_f32_e32 vcc, s85, v161
	s_nop 1
	v_cndmask_b32_e32 v161, v161, v189, vcc
	v_sqrt_f32_e32 v189, v161
	s_nop 0
	v_add_u32_e32 v191, -1, v189
	v_add_u32_e32 v234, 1, v189
	v_fma_f32 v235, -v191, v189, v161
	v_fma_f32 v188, -v234, v189, v161
	v_cmp_ge_f32_e64 s[80:81], 0, v235
	s_nop 1
	v_cndmask_b32_e64 v189, v189, v191, s[80:81]
	v_cmp_lt_f32_e64 s[80:81], 0, v188
	s_nop 1
	v_cndmask_b32_e64 v189, v189, v234, s[80:81]
	v_mul_f32_e32 v191, 0x37800000, v189
	v_cndmask_b32_e32 v189, v189, v191, vcc
	v_cmp_class_f32_e32 vcc, v161, v3
	s_nop 1
	v_cndmask_b32_e32 v161, v189, v161, vcc
	v_div_scale_f32 v189, s[80:81], v161, v161, 1.0
	v_rcp_f32_e32 v234, v189
	v_div_scale_f32 v191, vcc, 1.0, v161, 1.0
	v_fma_f32 v235, -v189, v234, 1.0
	v_fmac_f32_e32 v234, v235, v234
	v_mul_f32_e32 v235, v191, v234
	v_fma_f32 v188, -v189, v235, v191
	v_fmac_f32_e32 v235, v188, v234
	v_fma_f32 v189, -v189, v235, v191
	v_div_fmas_f32 v189, v189, v234, v235
	v_div_fixup_f32 v220, v189, v161, 1.0
	v_pk_mul_f32 v[222:223], v[148:149], v[220:221] op_sel_hi:[1,0]
	v_pk_mul_f32 v[224:225], v[150:151], v[220:221] op_sel_hi:[1,0]
	v_pk_mul_f32 v[222:223], v[48:49], v[222:223]
	v_pk_mul_f32 v[224:225], v[50:51], v[224:225]
	v_cvt_pk_bf16_f32 v226, v222, v223
	v_cvt_pk_bf16_f32 v227, v224, v225
	global_store_dwordx2 v0, v[226:227], s[78:79] offset:0
	v_pk_mul_f32 v[222:223], v[152:153], v[220:221] op_sel_hi:[1,0]
	v_pk_mul_f32 v[224:225], v[154:155], v[220:221] op_sel_hi:[1,0]
	v_pk_mul_f32 v[222:223], v[52:53], v[222:223]
	v_pk_mul_f32 v[224:225], v[54:55], v[224:225]
	v_cvt_pk_bf16_f32 v228, v222, v223
	v_cvt_pk_bf16_f32 v229, v224, v225
	global_store_dwordx2 v0, v[228:229], s[78:79] offset:512
	v_pk_mul_f32 v[222:223], v[156:157], v[220:221] op_sel_hi:[1,0]
	v_pk_mul_f32 v[224:225], v[158:159], v[220:221] op_sel_hi:[1,0]
	v_pk_mul_f32 v[222:223], v[56:57], v[222:223]
	v_pk_mul_f32 v[224:225], v[58:59], v[224:225]
	v_cvt_pk_bf16_f32 v230, v222, v223
	v_cvt_pk_bf16_f32 v231, v224, v225
	global_store_dwordx2 v0, v[230:231], s[78:79] offset:1024
	v_pk_mul_f32 v[222:223], v[164:165], v[220:221] op_sel_hi:[1,0]
	v_pk_mul_f32 v[224:225], v[166:167], v[220:221] op_sel_hi:[1,0]
	v_pk_mul_f32 v[222:223], v[60:61], v[222:223]
	v_pk_mul_f32 v[224:225], v[62:63], v[224:225]
	v_cvt_pk_bf16_f32 v232, v222, v223
	v_cvt_pk_bf16_f32 v233, v224, v225
	global_store_dwordx2 v0, v[232:233], s[78:79] offset:1536
	v_pk_mul_f32 v[222:223], v[168:169], v[220:221] op_sel_hi:[1,0]
	v_pk_mul_f32 v[224:225], v[170:171], v[220:221] op_sel_hi:[1,0]
	v_pk_mul_f32 v[222:223], v[64:65], v[222:223]
	v_pk_mul_f32 v[224:225], v[66:67], v[224:225]
	v_cvt_pk_bf16_f32 v226, v222, v223
	v_cvt_pk_bf16_f32 v227, v224, v225
	global_store_dwordx2 v0, v[226:227], s[78:79] offset:2048
	v_pk_mul_f32 v[222:223], v[172:173], v[220:221] op_sel_hi:[1,0]
	v_pk_mul_f32 v[224:225], v[174:175], v[220:221] op_sel_hi:[1,0]
	v_pk_mul_f32 v[222:223], v[68:69], v[222:223]
	v_pk_mul_f32 v[224:225], v[70:71], v[224:225]
	v_cvt_pk_bf16_f32 v228, v222, v223
	v_cvt_pk_bf16_f32 v229, v224, v225
	global_store_dwordx2 v0, v[228:229], s[78:79] offset:2560
	v_pk_mul_f32 v[222:223], v[176:177], v[220:221] op_sel_hi:[1,0]
	v_pk_mul_f32 v[224:225], v[178:179], v[220:221] op_sel_hi:[1,0]
	v_pk_mul_f32 v[222:223], v[72:73], v[222:223]
	v_pk_mul_f32 v[224:225], v[74:75], v[224:225]
	v_cvt_pk_bf16_f32 v230, v222, v223
	v_cvt_pk_bf16_f32 v231, v224, v225
	global_store_dwordx2 v0, v[230:231], s[78:79] offset:3072
	v_pk_mul_f32 v[222:223], v[180:181], v[220:221] op_sel_hi:[1,0]
	v_pk_mul_f32 v[224:225], v[182:183], v[220:221] op_sel_hi:[1,0]
	v_pk_mul_f32 v[222:223], v[76:77], v[222:223]
	v_pk_mul_f32 v[224:225], v[78:79], v[224:225]
	v_cvt_pk_bf16_f32 v232, v222, v223
	v_cvt_pk_bf16_f32 v233, v224, v225
	global_store_dwordx2 v0, v[232:233], s[78:79] offset:3584
	s_add_u32 s78, s78, s62
	s_addc_u32 s79, s79, 0
	s_mov_b32 s32, s84
	s_cmp_lt_u32 s32, 0x8000
	s_cbranch_scc1 .Lrow_rp1_top

; #define NTL(p) __builtin_nontemporal_load(&(p))
; __device__ __forceinline__ float bf_lo(unsigned u) { return __uint_as_float(u << 16); }
; __device__ __forceinline__ float bf_hi(unsigned u) { return __uint_as_float(u & 0xffff0000u); }
; template <bool HAS_H, bool XIN_BF, bool XOUT_BF>
; __device__ __forceinline__ void row_pass(const bf16_t* y, const void* xin, void* xout, const float* g_post, const float* g_pre, bf16_t* hout, int G, int blk) {
;     const int tid = threadIdx.x, lane = tid & 63, wave = tid >> 6;
;     const int gw = blk * 8 + wave, NGW = G * 8;
;     for (int row = gw; row < MT; row += NGW) {
;         const u32x2* yr = (const u32x2*)(y + (size_t)row * DM) + lane;
;         const f32x4* xr = (const f32x4*)((const float*)xin + (size_t)row * DM) + lane;
;         const u32x2* xrb = (const u32x2*)((const bf16_t*)xin + (size_t)row * DM) + lane;
;         f32x4 yv[8], xv[8]; float s = 0.f;
; #pragma unroll
;         for (int j = 0; j < 8; ++j) { const u32x2 w = NTL(yr[64 * j]); yv[j] = (f32x4){bf_lo(w.x), bf_hi(w.x), bf_lo(w.y), bf_hi(w.y)};
;             if (XIN_BF) { const u32x2 xw = NTL(xrb[64 * j]); xv[j] = (f32x4){bf_lo(xw.x), bf_hi(xw.x), bf_lo(xw.y), bf_hi(xw.y)}; } else xv[j] = NTL(xr[64 * j]);
;             s += (yv[j].x * yv[j].x + yv[j].y * yv[j].y) + (yv[j].z * yv[j].z + yv[j].w * yv[j].w); }
;         const float r = 1.0f / sqrtf(wave_sum(s) * (1.0f / DM) + EPS);
;         const f32x4* gp = (const f32x4*)g_post + lane;
;         f32x4* xo = (f32x4*)((float*)xout + (size_t)row * DM) + lane;
;         u32x2* xob = (u32x2*)((bf16_t*)xout + (size_t)row * DM) + lane;
.LBB0_758:
	v_readfirstlane_b32 s32, v128
	s_nop 3
	v_lshlrev_b32_e32 v4, 3, v163
	v_lshlrev_b32_e32 v5, 4, v163
	v_mov_b32_e32 v6, 0x358637bd
	v_mov_b32_e32 v7, 0x260
	s_mov_b32 s85, 0xf800000
	v_xor_b32_e32 v8, 1, v163
	v_xor_b32_e32 v9, 2, v163
	v_xor_b32_e32 v10, 4, v163
	v_xor_b32_e32 v11, 8, v163
	v_xor_b32_e32 v12, 16, v163
	v_xor_b32_e32 v13, 32, v163
	v_lshlrev_b32_e32 v8, 2, v8
	v_lshlrev_b32_e32 v9, 2, v9
	v_lshlrev_b32_e32 v10, 2, v10
	v_lshlrev_b32_e32 v11, 2, v11
	v_lshlrev_b32_e32 v12, 2, v12
	v_lshlrev_b32_e32 v13, 2, v13
	s_lshl_b32 s62, s94, 12
	s_lshl_b32 s63, s94, 13
	s_mov_b64 s[92:93], 0x1000
	global_load_dwordx4 v[16:19], v[0:1], off offset:0
	global_load_dwordx4 v[20:23], v[0:1], off offset:1024
	global_load_dwordx4 v[24:27], v[0:1], off offset:2048
	global_load_dwordx4 v[28:31], v[0:1], off offset:3072
	v_lshl_add_u64 v[236:237], v[0:1], 0, s[92:93]
	global_load_dwordx4 v[32:35], v[236:237], off offset:0
	global_load_dwordx4 v[36:39], v[236:237], off offset:1024
	global_load_dwordx4 v[40:43], v[236:237], off offset:2048
	global_load_dwordx4 v[44:47], v[236:237], off offset:3072
	global_load_dwordx4 v[48:51], v[2:3], off offset:0
	global_load_dwordx4 v[52:55], v[2:3], off offset:1024
	global_load_dwordx4 v[56:59], v[2:3], off offset:2048
	global_load_dwordx4 v[60:63], v[2:3], off offset:3072
	v_lshl_add_u64 v[236:237], v[2:3], 0, s[92:93]
	global_load_dwordx4 v[64:67], v[236:237], off offset:0
	global_load_dwordx4 v[68:71], v[236:237], off offset:1024
	global_load_dwordx4 v[72:75], v[236:237], off offset:2048
	global_load_dwordx4 v[76:79], v[236:237], off offset:3072
	s_add_u32 s24, s28, 0x2a000000
	s_addc_u32 s25, s29, 0
	s_lshl_b32 s92, s32, 12
	s_add_u32 s24, s24, s92
	s_addc_u32 s25, s25, 0
	s_add_u32 s26, s28, 0x36000000
	s_addc_u32 s27, s29, 0
	s_lshl_b32 s92, s32, 12
	s_add_u32 s26, s26, s92
	s_addc_u32 s27, s27, 0
	s_add_u32 s70, s28, 0x36000000
	s_addc_u32 s71, s29, 0
	s_lshl_b32 s92, s32, 12
	s_add_u32 s70, s70, s92
	s_addc_u32 s71, s71, 0
	s_add_u32 s78, s28, 0xe000000
	s_addc_u32 s79, s29, 0
	s_lshl_b32 s92, s32, 12
	s_add_u32 s78, s78, s92
	s_addc_u32 s79, s79, 0
	global_load_dwordx2 v[14:15], v4, s[24:25] offset:0 nt
	global_load_dwordx2 v[80:81], v4, s[24:25] offset:512 nt
	global_load_dwordx2 v[82:83], v4, s[24:25] offset:1024 nt
	global_load_dwordx2 v[84:85], v4, s[24:25] offset:1536 nt
	global_load_dwordx2 v[86:87], v4, s[24:25] offset:2048 nt
	global_load_dwordx2 v[88:89], v4, s[24:25] offset:2560 nt
	global_load_dwordx2 v[90:91], v4, s[24:25] offset:3072 nt
	global_load_dwordx2 v[92:93], v4, s[24:25] offset:3584 nt
	global_load_dwordx2 v[110:111], v4, s[26:27] offset:0
	global_load_dwordx2 v[112:113], v4, s[26:27] offset:512
	global_load_dwordx2 v[114:115], v4, s[26:27] offset:1024
	global_load_dwordx2 v[116:117], v4, s[26:27] offset:1536
	global_load_dwordx2 v[118:119], v4, s[26:27] offset:2048
	global_load_dwordx2 v[120:121], v4, s[26:27] offset:2560
	global_load_dwordx2 v[122:123], v4, s[26:27] offset:3072
	global_load_dwordx2 v[124:125], v4, s[26:27] offset:3584
	s_add_u32 s24, s24, s62
	s_addc_u32 s25, s25, 0
	s_add_u32 s26, s26, s62
	s_addc_u32 s27, s27, 0
	s_add_u32 s84, s32, s94
	s_cmp_lt_u32 s84, 0x8000
	s_cbranch_scc0 .Lrow_rp2_first_last
	global_load_dwordx2 v[94:95], v4, s[24:25] offset:0 nt
	global_load_dwordx2 v[96:97], v4, s[24:25] offset:512 nt
	global_load_dwordx2 v[98:99], v4, s[24:25] offset:1024 nt
	global_load_dwordx2 v[100:101], v4, s[24:25] offset:1536 nt
	global_load_dwordx2 v[102:103], v4, s[24:25] offset:2048 nt
	global_load_dwordx2 v[104:105], v4, s[24:25] offset:2560 nt
	global_load_dwordx2 v[106:107], v4, s[24:25] offset:3072 nt
	global_load_dwordx2 v[108:109], v4, s[24:25] offset:3584 nt
	global_load_dwordx2 v[126:127], v4, s[26:27] offset:0
	global_load_dwordx2 v[130:131], v4, s[26:27] offset:512
	global_load_dwordx2 v[132:133], v4, s[26:27] offset:1024
	global_load_dwordx2 v[134:135], v4, s[26:27] offset:1536
	global_load_dwordx2 v[136:137], v4, s[26:27] offset:2048
	global_load_dwordx2 v[138:139], v4, s[26:27] offset:2560
	global_load_dwordx2 v[140:141], v4, s[26:27] offset:3072
	global_load_dwordx2 v[142:143], v4, s[26:27] offset:3584
	s_add_u32 s24, s24, s62
	s_addc_u32 s25, s25, 0
	s_add_u32 s26, s26, s62
	s_addc_u32 s27, s27, 0
	s_waitcnt vmcnt(16)
	s_branch .Lrow_rp2_compA

; #define NTL(p) __builtin_nontemporal_load(&(p))
; __device__ __forceinline__ float bf_lo(unsigned u) { return __uint_as_float(u << 16); }
; __device__ __forceinline__ float bf_hi(unsigned u) { return __uint_as_float(u & 0xffff0000u); }
; template <bool HAS_H, bool XIN_BF, bool XOUT_BF>
; __device__ __forceinline__ void row_pass(const bf16_t* y, const void* xin, void* xout, const float* g_post, const float* g_pre, bf16_t* hout, int G, int blk) {
;     ...
;     for (int row = gw; row < MT; row += NGW) {
;         const u32x2* yr = (const u32x2*)(y + (size_t)row * DM) + lane;
;         const f32x4* xr = (const f32x4*)((const float*)xin + (size_t)row * DM) + lane;
;         const u32x2* xrb = (const u32x2*)((const bf16_t*)xin + (size_t)row * DM) + lane;
;         f32x4 yv[8], xv[8]; float s = 0.f;
; #pragma unroll
;         for (int j = 0; j < 8; ++j) { const u32x2 w = NTL(yr[64 * j]); yv[j] = (f32x4){bf_lo(w.x), bf_hi(w.x), bf_lo(w.y), bf_hi(w.y)};
;             if (XIN_BF) { const u32x2 xw = NTL(xrb[64 * j]); xv[j] = (f32x4){bf_lo(xw.x), bf_hi(xw.x), bf_lo(xw.y), bf_hi(xw.y)}; } else xv[j] = NTL(xr[64 * j]);
;             s += (yv[j].x * yv[j].x + yv[j].y * yv[j].y) + (yv[j].z * yv[j].z + yv[j].w * yv[j].w); }
.Lrow_rp2_top:
	s_add_u32 s84, s32, s94
	s_cmp_lt_u32 s84, 0x8000
	s_cbranch_scc0 .Lrow_rp2_lastA
	global_load_dwordx2 v[94:95], v4, s[24:25] offset:0 nt
	global_load_dwordx2 v[96:97], v4, s[24:25] offset:512 nt
	global_load_dwordx2 v[98:99], v4, s[24:25] offset:1024 nt
	global_load_dwordx2 v[100:101], v4, s[24:25] offset:1536 nt
	global_load_dwordx2 v[102:103], v4, s[24:25] offset:2048 nt
	global_load_dwordx2 v[104:105], v4, s[24:25] offset:2560 nt
	global_load_dwordx2 v[106:107], v4, s[24:25] offset:3072 nt
	global_load_dwordx2 v[108:109], v4, s[24:25] offset:3584 nt
	global_load_dwordx2 v[126:127], v4, s[26:27] offset:0
	global_load_dwordx2 v[130:131], v4, s[26:27] offset:512
	global_load_dwordx2 v[132:133], v4, s[26:27] offset:1024
	global_load_dwordx2 v[134:135], v4, s[26:27] offset:1536
	global_load_dwordx2 v[136:137], v4, s[26:27] offset:2048
	global_load_dwordx2 v[138:139], v4, s[26:27] offset:2560
	global_load_dwordx2 v[140:141], v4, s[26:27] offset:3072
	global_load_dwordx2 v[142:143], v4, s[26:27] offset:3584
	s_add_u32 s24, s24, s62
	s_addc_u32 s25, s25, 0
	s_add_u32 s26, s26, s62
	s_addc_u32 s27, s27, 0
	s_waitcnt vmcnt(32)
	s_branch .Lrow_rp2_compA

; __device__ __forceinline__ unsigned cvtpk(float lo, float hi) { f32x2_t v = {lo, hi}; bf16x2_t b = __builtin_convertvector(v, bf16x2_t); return __builtin_bit_cast(unsigned, b); }
; #define NTL(p) __builtin_nontemporal_load(&(p))
; #define NTS(v, p) __builtin_nontemporal_store((v), &(p))
; __device__ __forceinline__ float bf_lo(unsigned u) { return __uint_as_float(u << 16); }
; __device__ __forceinline__ float bf_hi(unsigned u) { return __uint_as_float(u & 0xffff0000u); }
; template <bool HAS_H, bool XIN_BF, bool XOUT_BF>
; __device__ __forceinline__ void row_pass(const bf16_t* y, const void* xin, void* xout, const float* g_post, const float* g_pre, bf16_t* hout, int G, int blk) {
;     ...
;         for (int j = 0; j < 8; ++j) { const u32x2 w = NTL(yr[64 * j]); yv[j] = (f32x4){bf_lo(w.x), bf_hi(w.x), bf_lo(w.y), bf_hi(w.y)};
;             if (XIN_BF) { const u32x2 xw = NTL(xrb[64 * j]); xv[j] = (f32x4){bf_lo(xw.x), bf_hi(xw.x), bf_lo(xw.y), bf_hi(xw.y)}; } else xv[j] = NTL(xr[64 * j]);
;             s += (yv[j].x * yv[j].x + yv[j].y * yv[j].y) + (yv[j].z * yv[j].z + yv[j].w * yv[j].w); }
;         const float r = 1.0f / sqrtf(wave_sum(s) * (1.0f / DM) + EPS);
;         const f32x4* gp = (const f32x4*)g_post + lane;
;         f32x4* xo = (f32x4*)((float*)xout + (size_t)row * DM) + lane;
;         u32x2* xob = (u32x2*)((bf16_t*)xout + (size_t)row * DM) + lane;
;         float s1 = 0.f;
; #pragma unroll
;         for (int j = 0; j < 8; ++j) { const f32x4 gv = gp[64 * j]; xv[j] = xv[j] + yv[j] * r * gv;
;             if (XOUT_BF) { u32x2 w; w.x = cvtpk(xv[j].x, xv[j].y); w.y = cvtpk(xv[j].z, xv[j].w); NTS(w, xob[64 * j]); } else NTS(xv[j], xo[64 * j]);
.Lrow_rp2_compA:
	v_lshlrev_b32_e32 v144, 16, v110
	v_and_b32_e32 v145, 0xffff0000, v110
	v_lshlrev_b32_e32 v146, 16, v111
	v_and_b32_e32 v147, 0xffff0000, v111
	v_lshlrev_b32_e32 v148, 16, v112
	v_and_b32_e32 v149, 0xffff0000, v112
	v_lshlrev_b32_e32 v150, 16, v113
	v_and_b32_e32 v151, 0xffff0000, v113
	v_lshlrev_b32_e32 v152, 16, v114
	v_and_b32_e32 v153, 0xffff0000, v114
	v_lshlrev_b32_e32 v154, 16, v115
	v_and_b32_e32 v155, 0xffff0000, v115
	v_lshlrev_b32_e32 v156, 16, v116
	v_and_b32_e32 v157, 0xffff0000, v116
	v_lshlrev_b32_e32 v158, 16, v117
	v_and_b32_e32 v159, 0xffff0000, v117
	v_lshlrev_b32_e32 v164, 16, v118
	v_and_b32_e32 v165, 0xffff0000, v118
	v_lshlrev_b32_e32 v166, 16, v119
	v_and_b32_e32 v167, 0xffff0000, v119
	v_lshlrev_b32_e32 v168, 16, v120
	v_and_b32_e32 v169, 0xffff0000, v120
	v_lshlrev_b32_e32 v170, 16, v121
	v_and_b32_e32 v171, 0xffff0000, v121
	v_lshlrev_b32_e32 v172, 16, v122
	v_and_b32_e32 v173, 0xffff0000, v122
	v_lshlrev_b32_e32 v174, 16, v123
	v_and_b32_e32 v175, 0xffff0000, v123
	v_lshlrev_b32_e32 v176, 16, v124
	v_and_b32_e32 v177, 0xffff0000, v124
	v_lshlrev_b32_e32 v178, 16, v125
	v_and_b32_e32 v179, 0xffff0000, v125
	v_lshlrev_b32_e32 v180, 16, v14
	v_and_b32_e32 v181, 0xffff0000, v14
	v_lshlrev_b32_e32 v182, 16, v15
	v_and_b32_e32 v183, 0xffff0000, v15
	v_lshlrev_b32_e32 v184, 16, v80
	v_and_b32_e32 v185, 0xffff0000, v80
	v_lshlrev_b32_e32 v186, 16, v81
	v_and_b32_e32 v187, 0xffff0000, v81
	v_lshlrev_b32_e32 v192, 16, v82
	v_and_b32_e32 v193, 0xffff0000, v82
	v_lshlrev_b32_e32 v194, 16, v83
	v_and_b32_e32 v195, 0xffff0000, v83
	v_lshlrev_b32_e32 v196, 16, v84
	v_and_b32_e32 v197, 0xffff0000, v84
	v_lshlrev_b32_e32 v198, 16, v85
	v_and_b32_e32 v199, 0xffff0000, v85
	v_lshlrev_b32_e32 v200, 16, v86
	v_and_b32_e32 v201, 0xffff0000, v86
	v_lshlrev_b32_e32 v202, 16, v87
	v_and_b32_e32 v203, 0xffff0000, v87
	v_lshlrev_b32_e32 v204, 16, v88
	v_and_b32_e32 v205, 0xffff0000, v88
	v_lshlrev_b32_e32 v206, 16, v89
	v_and_b32_e32 v207, 0xffff0000, v89
	v_lshlrev_b32_e32 v208, 16, v90
	v_and_b32_e32 v209, 0xffff0000, v90
	v_lshlrev_b32_e32 v210, 16, v91
	v_and_b32_e32 v211, 0xffff0000, v91
	v_lshlrev_b32_e32 v212, 16, v92
	v_and_b32_e32 v213, 0xffff0000, v92
	v_lshlrev_b32_e32 v214, 16, v93
	v_and_b32_e32 v215, 0xffff0000, v93
	v_pk_mul_f32 v[188:189], v[180:181], v[180:181]
	v_pk_mul_f32 v[216:217], v[182:183], v[182:183]
	v_pk_fma_f32 v[188:189], v[184:185], v[184:185], v[188:189]
	v_pk_fma_f32 v[216:217], v[186:187], v[186:187], v[216:217]
	v_pk_fma_f32 v[188:189], v[192:193], v[192:193], v[188:189]
	v_pk_fma_f32 v[216:217], v[194:195], v[194:195], v[216:217]
	v_pk_fma_f32 v[188:189], v[196:197], v[196:197], v[188:189]
	v_pk_fma_f32 v[216:217], v[198:199], v[198:199], v[216:217]
	v_pk_fma_f32 v[188:189], v[200:201], v[200:201], v[188:189]
	v_pk_fma_f32 v[216:217], v[202:203], v[202:203], v[216:217]
	v_pk_fma_f32 v[188:189], v[204:205], v[204:205], v[188:189]
	v_pk_fma_f32 v[216:217], v[206:207], v[206:207], v[216:217]
	v_pk_fma_f32 v[188:189], v[208:209], v[208:209], v[188:189]
	v_pk_fma_f32 v[216:217], v[210:211], v[210:211], v[216:217]
	v_pk_fma_f32 v[188:189], v[212:213], v[212:213], v[188:189]
	v_pk_fma_f32 v[216:217], v[214:215], v[214:215], v[216:217]
	v_pk_add_f32 v[188:189], v[188:189], v[216:217]
	s_nop 0
	v_add_f32_e32 v161, v188, v189
	ds_bpermute_b32 v191, v8, v161
	s_waitcnt lgkmcnt(0)
	v_add_f32_e32 v161, v161, v191
	ds_bpermute_b32 v191, v9, v161
	s_waitcnt lgkmcnt(0)
	v_add_f32_e32 v161, v161, v191
	ds_bpermute_b32 v191, v10, v161
	s_waitcnt lgkmcnt(0)
	v_add_f32_e32 v161, v161, v191
	ds_bpermute_b32 v191, v11, v161
	s_waitcnt lgkmcnt(0)
	v_add_f32_e32 v161, v161, v191
	ds_bpermute_b32 v191, v12, v161
	s_waitcnt lgkmcnt(0)
	v_add_f32_e32 v161, v161, v191
	ds_bpermute_b32 v191, v13, v161
	s_waitcnt lgkmcnt(0)
	v_add_f32_e32 v161, v161, v191
	v_fmamk_f32 v161, v161, 0x3a000000, v6
	v_mul_f32_e32 v232, 0x4f800000, v161
	v_cmp_gt_f32_e32 vcc, s85, v161
	s_nop 1
	v_cndmask_b32_e32 v161, v161, v232, vcc
	v_sqrt_f32_e32 v232, v161
	s_nop 0
	v_add_u32_e32 v233, -1, v232
	v_add_u32_e32 v234, 1, v232
	v_fma_f32 v235, -v233, v232, v161
	v_fma_f32 v191, -v234, v232, v161
	v_cmp_ge_f32_e64 s[80:81], 0, v235
	s_nop 1
	v_cndmask_b32_e64 v232, v232, v233, s[80:81]
	v_cmp_lt_f32_e64 s[80:81], 0, v191
	s_nop 1
	v_cndmask_b32_e64 v232, v232, v234, s[80:81]
	v_mul_f32_e32 v233, 0x37800000, v232
	v_cndmask_b32_e32 v232, v232, v233, vcc
	v_cmp_class_f32_e32 vcc, v161, v7
	s_nop 1
	v_cndmask_b32_e32 v161, v232, v161, vcc
	v_div_scale_f32 v232, s[80:81], v161, v161, 1.0
	v_rcp_f32_e32 v234, v232
	v_div_scale_f32 v233, vcc, 1.0, v161, 1.0
	v_fma_f32 v235, -v232, v234, 1.0
	v_fmac_f32_e32 v234, v235, v234
	v_mul_f32_e32 v235, v233, v234
	v_fma_f32 v191, -v232, v235, v233
	v_fmac_f32_e32 v235, v191, v234
	v_fma_f32 v232, -v232, v235, v233
	v_div_fmas_f32 v232, v232, v234, v235
	v_div_fixup_f32 v218, v232, v161, 1.0
	v_pk_mul_f32 v[220:221], v[180:181], v[218:219] op_sel_hi:[1,0]
	v_pk_mul_f32 v[222:223], v[182:183], v[218:219] op_sel_hi:[1,0]
	v_pk_fma_f32 v[144:145], v[16:17], v[220:221], v[144:145]
	v_pk_fma_f32 v[146:147], v[18:19], v[222:223], v[146:147]
	v_cvt_pk_bf16_f32 v224, v144, v145
	v_cvt_pk_bf16_f32 v225, v146, v147
	global_store_dwordx2 v4, v[224:225], s[70:71] offset:0 nt
	v_pk_mul_f32 v[220:221], v[184:185], v[218:219] op_sel_hi:[1,0]
	v_pk_mul_f32 v[222:223], v[186:187], v[218:219] op_sel_hi:[1,0]
	v_pk_fma_f32 v[148:149], v[20:21], v[220:221], v[148:149]
	v_pk_fma_f32 v[150:151], v[22:23], v[222:223], v[150:151]
	v_cvt_pk_bf16_f32 v226, v148, v149
	v_cvt_pk_bf16_f32 v227, v150, v151
; __device__ __forceinline__ unsigned cvtpk(float lo, float hi) { f32x2_t v = {lo, hi}; bf16x2_t b = __builtin_convertvector(v, bf16x2_t); return __builtin_bit_cast(unsigned, b); }
; #define NTS(v, p) __builtin_nontemporal_store((v), &(p))
; template <bool HAS_H, bool XIN_BF, bool XOUT_BF>
; __device__ __forceinline__ void row_pass(const bf16_t* y, const void* xin, void* xout, const float* g_post, const float* g_pre, bf16_t* hout, int G, int blk) {
;     ...
;         for (int j = 0; j < 8; ++j) { const f32x4 gv = gp[64 * j]; xv[j] = xv[j] + yv[j] * r * gv;
;             if (XOUT_BF) { u32x2 w; w.x = cvtpk(xv[j].x, xv[j].y); w.y = cvtpk(xv[j].z, xv[j].w); NTS(w, xob[64 * j]); } else NTS(xv[j], xo[64 * j]);
;             s1 += (xv[j].x * xv[j].x + xv[j].y * xv[j].y) + (xv[j].z * xv[j].z + xv[j].w * xv[j].w); }
;         if (HAS_H) {
;             const float r1 = 1.0f / sqrtf(wave_sum(s1) * (1.0f / DM) + EPS);
	global_store_dwordx2 v4, v[226:227], s[70:71] offset:512 nt
	v_pk_mul_f32 v[220:221], v[192:193], v[218:219] op_sel_hi:[1,0]
	v_pk_mul_f32 v[222:223], v[194:195], v[218:219] op_sel_hi:[1,0]
	v_pk_fma_f32 v[152:153], v[24:25], v[220:221], v[152:153]
	v_pk_fma_f32 v[154:155], v[26:27], v[222:223], v[154:155]
	v_cvt_pk_bf16_f32 v228, v152, v153
	v_cvt_pk_bf16_f32 v229, v154, v155
	global_store_dwordx2 v4, v[228:229], s[70:71] offset:1024 nt
	v_pk_mul_f32 v[220:221], v[196:197], v[218:219] op_sel_hi:[1,0]
	v_pk_mul_f32 v[222:223], v[198:199], v[218:219] op_sel_hi:[1,0]
	v_pk_fma_f32 v[156:157], v[28:29], v[220:221], v[156:157]
	v_pk_fma_f32 v[158:159], v[30:31], v[222:223], v[158:159]
	v_cvt_pk_bf16_f32 v230, v156, v157
	v_cvt_pk_bf16_f32 v231, v158, v159
	global_store_dwordx2 v4, v[230:231], s[70:71] offset:1536 nt
	v_pk_mul_f32 v[220:221], v[200:201], v[218:219] op_sel_hi:[1,0]
	v_pk_mul_f32 v[222:223], v[202:203], v[218:219] op_sel_hi:[1,0]
	v_pk_fma_f32 v[164:165], v[32:33], v[220:221], v[164:165]
	v_pk_fma_f32 v[166:167], v[34:35], v[222:223], v[166:167]
	v_cvt_pk_bf16_f32 v224, v164, v165
	v_cvt_pk_bf16_f32 v225, v166, v167
	global_store_dwordx2 v4, v[224:225], s[70:71] offset:2048 nt
	v_pk_mul_f32 v[220:221], v[204:205], v[218:219] op_sel_hi:[1,0]
	v_pk_mul_f32 v[222:223], v[206:207], v[218:219] op_sel_hi:[1,0]
	v_pk_fma_f32 v[168:169], v[36:37], v[220:221], v[168:169]
	v_pk_fma_f32 v[170:171], v[38:39], v[222:223], v[170:171]
	v_cvt_pk_bf16_f32 v226, v168, v169
	v_cvt_pk_bf16_f32 v227, v170, v171
	global_store_dwordx2 v4, v[226:227], s[70:71] offset:2560 nt
	v_pk_mul_f32 v[220:221], v[208:209], v[218:219] op_sel_hi:[1,0]
	v_pk_mul_f32 v[222:223], v[210:211], v[218:219] op_sel_hi:[1,0]
	v_pk_fma_f32 v[172:173], v[40:41], v[220:221], v[172:173]
	v_pk_fma_f32 v[174:175], v[42:43], v[222:223], v[174:175]
	v_cvt_pk_bf16_f32 v228, v172, v173
	v_cvt_pk_bf16_f32 v229, v174, v175
	global_store_dwordx2 v4, v[228:229], s[70:71] offset:3072 nt
	v_pk_mul_f32 v[220:221], v[212:213], v[218:219] op_sel_hi:[1,0]
	v_pk_mul_f32 v[222:223], v[214:215], v[218:219] op_sel_hi:[1,0]
	v_pk_fma_f32 v[176:177], v[44:45], v[220:221], v[176:177]
	v_pk_fma_f32 v[178:179], v[46:47], v[222:223], v[178:179]
	v_cvt_pk_bf16_f32 v230, v176, v177
	v_cvt_pk_bf16_f32 v231, v178, v179
	global_store_dwordx2 v4, v[230:231], s[70:71] offset:3584 nt
	s_add_u32 s70, s70, s62
	s_addc_u32 s71, s71, 0
	v_pk_mul_f32 v[188:189], v[144:145], v[144:145]
	v_pk_mul_f32 v[216:217], v[146:147], v[146:147]
	v_pk_fma_f32 v[188:189], v[148:149], v[148:149], v[188:189]
	v_pk_fma_f32 v[216:217], v[150:151], v[150:151], v[216:217]
	v_pk_fma_f32 v[188:189], v[152:153], v[152:153], v[188:189]
	v_pk_fma_f32 v[216:217], v[154:155], v[154:155], v[216:217]
	v_pk_fma_f32 v[188:189], v[156:157], v[156:157], v[188:189]
	v_pk_fma_f32 v[216:217], v[158:159], v[158:159], v[216:217]
	v_pk_fma_f32 v[188:189], v[164:165], v[164:165], v[188:189]
	v_pk_fma_f32 v[216:217], v[166:167], v[166:167], v[216:217]
	v_pk_fma_f32 v[188:189], v[168:169], v[168:169], v[188:189]
	v_pk_fma_f32 v[216:217], v[170:171], v[170:171], v[216:217]
	v_pk_fma_f32 v[188:189], v[172:173], v[172:173], v[188:189]
	v_pk_fma_f32 v[216:217], v[174:175], v[174:175], v[216:217]
	v_pk_fma_f32 v[188:189], v[176:177], v[176:177], v[188:189]
	v_pk_fma_f32 v[216:217], v[178:179], v[178:179], v[216:217]
	v_pk_add_f32 v[188:189], v[188:189], v[216:217]
	s_nop 0
	v_add_f32_e32 v161, v188, v189
	ds_bpermute_b32 v191, v8, v161
	s_waitcnt lgkmcnt(0)
	v_add_f32_e32 v161, v161, v191
	ds_bpermute_b32 v191, v9, v161
	s_waitcnt lgkmcnt(0)
	v_add_f32_e32 v161, v161, v191
	ds_bpermute_b32 v191, v10, v161
	s_waitcnt lgkmcnt(0)
	v_add_f32_e32 v161, v161, v191
	ds_bpermute_b32 v191, v11, v161
	s_waitcnt lgkmcnt(0)
	v_add_f32_e32 v161, v161, v191
	ds_bpermute_b32 v191, v12, v161
	s_waitcnt lgkmcnt(0)
	v_add_f32_e32 v161, v161, v191
	ds_bpermute_b32 v191, v13, v161
	s_waitcnt lgkmcnt(0)
; __device__ __forceinline__ unsigned cvtpk(float lo, float hi) { f32x2_t v = {lo, hi}; bf16x2_t b = __builtin_convertvector(v, bf16x2_t); return __builtin_bit_cast(unsigned, b); }
; #define NTL(p) __builtin_nontemporal_load(&(p))
; __device__ __forceinline__ float bf_lo(unsigned u) { return __uint_as_float(u << 16); }
; __device__ __forceinline__ float bf_hi(unsigned u) { return __uint_as_float(u & 0xffff0000u); }
; template <bool HAS_H, bool XIN_BF, bool XOUT_BF>
; __device__ __forceinline__ void row_pass(const bf16_t* y, const void* xin, void* xout, const float* g_post, const float* g_pre, bf16_t* hout, int G, int blk) {
;     ...
;     for (int row = gw; row < MT; row += NGW) {
;         const u32x2* yr = (const u32x2*)(y + (size_t)row * DM) + lane;
;         const f32x4* xr = (const f32x4*)((const float*)xin + (size_t)row * DM) + lane;
;         const u32x2* xrb = (const u32x2*)((const bf16_t*)xin + (size_t)row * DM) + lane;
;         f32x4 yv[8], xv[8]; float s = 0.f;
; #pragma unroll
;         for (int j = 0; j < 8; ++j) { const u32x2 w = NTL(yr[64 * j]); yv[j] = (f32x4){bf_lo(w.x), bf_hi(w.x), bf_lo(w.y), bf_hi(w.y)};
;             if (XIN_BF) { const u32x2 xw = NTL(xrb[64 * j]); xv[j] = (f32x4){bf_lo(xw.x), bf_hi(xw.x), bf_lo(xw.y), bf_hi(xw.y)}; } else xv[j] = NTL(xr[64 * j]);
;     ...
;             const float r1 = 1.0f / sqrtf(wave_sum(s1) * (1.0f / DM) + EPS);
;             const f32x4* gq = (const f32x4*)g_pre + lane;
;             u32x2* ho = (u32x2*)(hout + (size_t)row * DM) + lane;
; #pragma unroll
;             for (int j = 0; j < 8; ++j) { const f32x4 gv = gq[64 * j]; u32x2 w; w.x = cvtpk(xv[j].x * r1 * gv.x, xv[j].y * r1 * gv.y); w.y = cvtpk(xv[j].z * r1 * gv.z, xv[j].w * r1 * gv.w); ho[64 * j] = w; }
;         }
	v_add_f32_e32 v161, v161, v191
	v_fmamk_f32 v161, v161, 0x3a000000, v6
	v_mul_f32_e32 v232, 0x4f800000, v161
	v_cmp_gt_f32_e32 vcc, s85, v161
	s_nop 1
	v_cndmask_b32_e32 v161, v161, v232, vcc
	v_sqrt_f32_e32 v232, v161
	s_nop 0
	v_add_u32_e32 v233, -1, v232
	v_add_u32_e32 v234, 1, v232
	v_fma_f32 v235, -v233, v232, v161
	v_fma_f32 v191, -v234, v232, v161
	v_cmp_ge_f32_e64 s[80:81], 0, v235
	s_nop 1
	v_cndmask_b32_e64 v232, v232, v233, s[80:81]
	v_cmp_lt_f32_e64 s[80:81], 0, v191
	s_nop 1
	v_cndmask_b32_e64 v232, v232, v234, s[80:81]
	v_mul_f32_e32 v233, 0x37800000, v232
	v_cndmask_b32_e32 v232, v232, v233, vcc
	v_cmp_class_f32_e32 vcc, v161, v7
	s_nop 1
	v_cndmask_b32_e32 v161, v232, v161, vcc
	v_div_scale_f32 v232, s[80:81], v161, v161, 1.0
	v_rcp_f32_e32 v234, v232
	v_div_scale_f32 v233, vcc, 1.0, v161, 1.0
	v_fma_f32 v235, -v232, v234, 1.0
	v_fmac_f32_e32 v234, v235, v234
	v_mul_f32_e32 v235, v233, v234
	v_fma_f32 v191, -v232, v235, v233
	v_fmac_f32_e32 v235, v191, v234
	v_fma_f32 v232, -v232, v235, v233
	v_div_fmas_f32 v232, v232, v234, v235
	v_div_fixup_f32 v218, v232, v161, 1.0
	v_pk_mul_f32 v[220:221], v[144:145], v[218:219] op_sel_hi:[1,0]
	v_pk_mul_f32 v[222:223], v[146:147], v[218:219] op_sel_hi:[1,0]
	v_pk_mul_f32 v[220:221], v[48:49], v[220:221]
	v_pk_mul_f32 v[222:223], v[50:51], v[222:223]
	v_cvt_pk_bf16_f32 v224, v220, v221
	v_cvt_pk_bf16_f32 v225, v222, v223
	global_store_dwordx2 v4, v[224:225], s[78:79] offset:0
	v_pk_mul_f32 v[220:221], v[148:149], v[218:219] op_sel_hi:[1,0]
	v_pk_mul_f32 v[222:223], v[150:151], v[218:219] op_sel_hi:[1,0]
	v_pk_mul_f32 v[220:221], v[52:53], v[220:221]
	v_pk_mul_f32 v[222:223], v[54:55], v[222:223]
	v_cvt_pk_bf16_f32 v226, v220, v221
	v_cvt_pk_bf16_f32 v227, v222, v223
	global_store_dwordx2 v4, v[226:227], s[78:79] offset:512
	v_pk_mul_f32 v[220:221], v[152:153], v[218:219] op_sel_hi:[1,0]
	v_pk_mul_f32 v[222:223], v[154:155], v[218:219] op_sel_hi:[1,0]
	v_pk_mul_f32 v[220:221], v[56:57], v[220:221]
	v_pk_mul_f32 v[222:223], v[58:59], v[222:223]
	v_cvt_pk_bf16_f32 v228, v220, v221
	v_cvt_pk_bf16_f32 v229, v222, v223
	global_store_dwordx2 v4, v[228:229], s[78:79] offset:1024
	v_pk_mul_f32 v[220:221], v[156:157], v[218:219] op_sel_hi:[1,0]
	v_pk_mul_f32 v[222:223], v[158:159], v[218:219] op_sel_hi:[1,0]
	v_pk_mul_f32 v[220:221], v[60:61], v[220:221]
	v_pk_mul_f32 v[222:223], v[62:63], v[222:223]
	v_cvt_pk_bf16_f32 v230, v220, v221
	v_cvt_pk_bf16_f32 v231, v222, v223
	global_store_dwordx2 v4, v[230:231], s[78:79] offset:1536
	v_pk_mul_f32 v[220:221], v[164:165], v[218:219] op_sel_hi:[1,0]
	v_pk_mul_f32 v[222:223], v[166:167], v[218:219] op_sel_hi:[1,0]
	v_pk_mul_f32 v[220:221], v[64:65], v[220:221]
	v_pk_mul_f32 v[222:223], v[66:67], v[222:223]
	v_cvt_pk_bf16_f32 v224, v220, v221
	v_cvt_pk_bf16_f32 v225, v222, v223
	global_store_dwordx2 v4, v[224:225], s[78:79] offset:2048
	v_pk_mul_f32 v[220:221], v[168:169], v[218:219] op_sel_hi:[1,0]
	v_pk_mul_f32 v[222:223], v[170:171], v[218:219] op_sel_hi:[1,0]
	v_pk_mul_f32 v[220:221], v[68:69], v[220:221]
	v_pk_mul_f32 v[222:223], v[70:71], v[222:223]
	v_cvt_pk_bf16_f32 v226, v220, v221
	v_cvt_pk_bf16_f32 v227, v222, v223
	global_store_dwordx2 v4, v[226:227], s[78:79] offset:2560
	v_pk_mul_f32 v[220:221], v[172:173], v[218:219] op_sel_hi:[1,0]
	v_pk_mul_f32 v[222:223], v[174:175], v[218:219] op_sel_hi:[1,0]
	v_pk_mul_f32 v[220:221], v[72:73], v[220:221]
	v_pk_mul_f32 v[222:223], v[74:75], v[222:223]
	v_cvt_pk_bf16_f32 v228, v220, v221
	v_cvt_pk_bf16_f32 v229, v222, v223
	global_store_dwordx2 v4, v[228:229], s[78:79] offset:3072
	v_pk_mul_f32 v[220:221], v[176:177], v[218:219] op_sel_hi:[1,0]
	v_pk_mul_f32 v[222:223], v[178:179], v[218:219] op_sel_hi:[1,0]
	v_pk_mul_f32 v[220:221], v[76:77], v[220:221]
	v_pk_mul_f32 v[222:223], v[78:79], v[222:223]
	v_cvt_pk_bf16_f32 v230, v220, v221
	v_cvt_pk_bf16_f32 v231, v222, v223
	global_store_dwordx2 v4, v[230:231], s[78:79] offset:3584
	s_add_u32 s78, s78, s62
	s_addc_u32 s79, s79, 0
	s_mov_b32 s32, s84
	s_cmp_lt_u32 s32, 0x8000
	s_cbranch_scc0 .Lrow_rp2_done
	s_add_u32 s84, s32, s94
	s_cmp_lt_u32 s84, 0x8000
	s_cbranch_scc0 .Lrow_rp2_lastB
	global_load_dwordx2 v[14:15], v4, s[24:25] offset:0 nt
	global_load_dwordx2 v[80:81], v4, s[24:25] offset:512 nt
	global_load_dwordx2 v[82:83], v4, s[24:25] offset:1024 nt
	global_load_dwordx2 v[84:85], v4, s[24:25] offset:1536 nt
	global_load_dwordx2 v[86:87], v4, s[24:25] offset:2048 nt
	global_load_dwordx2 v[88:89], v4, s[24:25] offset:2560 nt
	global_load_dwordx2 v[90:91], v4, s[24:25] offset:3072 nt
	global_load_dwordx2 v[92:93], v4, s[24:25] offset:3584 nt
	global_load_dwordx2 v[110:111], v4, s[26:27] offset:0
	global_load_dwordx2 v[112:113], v4, s[26:27] offset:512
	global_load_dwordx2 v[114:115], v4, s[26:27] offset:1024
	global_load_dwordx2 v[116:117], v4, s[26:27] offset:1536
	global_load_dwordx2 v[118:119], v4, s[26:27] offset:2048
	global_load_dwordx2 v[120:121], v4, s[26:27] offset:2560
	global_load_dwordx2 v[122:123], v4, s[26:27] offset:3072
	global_load_dwordx2 v[124:125], v4, s[26:27] offset:3584
	s_add_u32 s24, s24, s62
	s_addc_u32 s25, s25, 0
	s_add_u32 s26, s26, s62
	s_addc_u32 s27, s27, 0
	s_waitcnt vmcnt(32)
	s_branch .Lrow_rp2_compB
